# v23 = v21 + S-phase work-queue ticket prefetched one item ahead (atomic round trip overlapped with item work)
# baseline (speedup 1.0000x reference)
.Ldq_pre_0:
	v_mov_b32_e32 v0, v117
	v_mbcnt_lo_u32_b32 v0, -1, v0
	v_mbcnt_hi_u32_b32 v0, -1, v0
	v_sub_u32_e32 v0, 0, v0
	v_cmp_eq_u32_e32 vcc, s33, v0
	s_and_saveexec_b64 s[0:1], vcc
	v_mov_b32_e32 v197, 1
	global_atomic_add v198, v117, v197, s[12:13] sc0
	s_or_b64 exec, exec, s[0:1]
	s_branch .LBB0_581
.LBB0_492:
	s_waitcnt vmcnt(0)
	s_add_i32 s75, s75, 1
	s_mov_b64 s[0:1], 0

.LBB0_581:
	v_mov_b32_e32 v0, v117
	s_waitcnt lgkmcnt(0)
	s_barrier
	v_mbcnt_lo_u32_b32 v0, -1, v0
	v_mbcnt_hi_u32_b32 v0, -1, v0
	v_sub_u32_e32 v0, 0, v0
	v_cmp_eq_u32_e32 vcc, s33, v0
	s_and_saveexec_b64 s[0:1], vcc
	s_cbranch_execz .LBB0_585
	s_waitcnt vmcnt(0)
	ds_write_b32 v117, v198 offset:59376
	v_mov_b32_e32 v197, 1
	global_atomic_add v198, v117, v197, s[12:13] sc0

.LBB0_1475:
	s_waitcnt vmcnt(0)
	s_add_i32 s77, s77, 1
	s_mov_b64 s[0:1], 0
